# phase 0 x conversion: 4 grid-strides per batch, two register sets software-pipelined (8-16 loads in flight per thread)
# baseline (speedup 1.0000x reference)
.LBB0_30:
	s_ashr_i32 s3, s2, 31
	v_mov_b32_e32 v6, v199
	v_writelane_b32 v242, s2, 45
	v_ashrrev_i32_e32 v7, 31, v6
	s_lshl_b64 s[0:1], s[2:3], 11
	v_lshl_add_u64 v[2:3], v[6:7], 3, s[0:1]
	s_mov_b64 s[0:1], 0x2000000
	v_cmp_gt_u64_e32 vcc, s[0:1], v[2:3]
	v_writelane_b32 v242, s3, 46
	s_and_saveexec_b64 s[0:1], vcc
	s_cbranch_execz .LBB0_33
	v_readlane_b32 s6, v242, 45
	s_ashr_i32 s97, s96, 31
	v_readlane_b32 s7, v242, 46
	s_lshl_b64 s[2:3], s[96:97], 11
	s_lshl_b64 s[4:5], s[6:7], 13
	s_add_u32 s4, s76, s4
	v_lshlrev_b64 v[4:5], 5, v[6:7]
	s_addc_u32 s5, s77, s5
	v_lshl_add_u64 v[4:5], s[4:5], 0, v[4:5]
	s_lshl_b64 s[4:5], s[96:97], 13
	s_lshl_b64 s[6:7], s[6:7], 12
	s_add_u32 s6, s94, s6
	s_addc_u32 s7, s95, s7
	v_lshl_add_u64 v[6:7], v[6:7], 4, s[6:7]
	s_mov_b64 s[6:7], 0x15000000
	v_lshl_add_u64 v[4:5], v[4:5], 0, 16
	v_lshl_add_u64 v[6:7], v[6:7], 0, s[6:7]
	s_lshl_b64 s[6:7], s[96:97], 12
	s_mov_b64 s[8:9], 0
	s_mov_b64 s[10:11], 0x1ffffff
	s_cmp_lg_u32 s96, 0x200
	s_cbranch_scc1 .LBB0_32
	global_load_dwordx4 v[16:19], v[4:5], off offset:-16
	global_load_dwordx4 v[20:23], v[4:5], off
	v_lshl_add_u64 v[4:5], v[4:5], 0, s[4:5]
	global_load_dwordx4 v[24:27], v[4:5], off offset:-16
	global_load_dwordx4 v[28:31], v[4:5], off
	v_lshl_add_u64 v[4:5], v[4:5], 0, s[4:5]
	global_load_dwordx4 v[32:35], v[4:5], off offset:-16
	global_load_dwordx4 v[36:39], v[4:5], off
	v_lshl_add_u64 v[4:5], v[4:5], 0, s[4:5]
	global_load_dwordx4 v[40:43], v[4:5], off offset:-16
	global_load_dwordx4 v[44:47], v[4:5], off
	v_lshl_add_u64 v[4:5], v[4:5], 0, s[4:5]
	s_mov_b32 s8, 3
.Lxc_loop:
	global_load_dwordx4 v[48:51], v[4:5], off offset:-16
	global_load_dwordx4 v[52:55], v[4:5], off
	v_lshl_add_u64 v[4:5], v[4:5], 0, s[4:5]
	global_load_dwordx4 v[56:59], v[4:5], off offset:-16
	global_load_dwordx4 v[60:63], v[4:5], off
	v_lshl_add_u64 v[4:5], v[4:5], 0, s[4:5]
	global_load_dwordx4 v[64:67], v[4:5], off offset:-16
	global_load_dwordx4 v[68:71], v[4:5], off
	v_lshl_add_u64 v[4:5], v[4:5], 0, s[4:5]
	global_load_dwordx4 v[72:75], v[4:5], off offset:-16
	global_load_dwordx4 v[76:79], v[4:5], off
	v_lshl_add_u64 v[4:5], v[4:5], 0, s[4:5]
	s_waitcnt vmcnt(8)
	v_cvt_pk_bf16_f32 v16, v16, v17
	v_cvt_pk_bf16_f32 v17, v18, v19
	v_cvt_pk_bf16_f32 v18, v20, v21
	v_cvt_pk_bf16_f32 v19, v22, v23
	global_store_dwordx4 v[6:7], v[16:19], off
	v_lshl_add_u64 v[6:7], v[6:7], 0, s[6:7]
	v_cvt_pk_bf16_f32 v24, v24, v25
	v_cvt_pk_bf16_f32 v25, v26, v27
	v_cvt_pk_bf16_f32 v26, v28, v29
	v_cvt_pk_bf16_f32 v27, v30, v31
	global_store_dwordx4 v[6:7], v[24:27], off
	v_lshl_add_u64 v[6:7], v[6:7], 0, s[6:7]
	v_cvt_pk_bf16_f32 v32, v32, v33
	v_cvt_pk_bf16_f32 v33, v34, v35
	v_cvt_pk_bf16_f32 v34, v36, v37
	v_cvt_pk_bf16_f32 v35, v38, v39
	global_store_dwordx4 v[6:7], v[32:35], off
	v_lshl_add_u64 v[6:7], v[6:7], 0, s[6:7]
	v_cvt_pk_bf16_f32 v40, v40, v41
	v_cvt_pk_bf16_f32 v41, v42, v43
	v_cvt_pk_bf16_f32 v42, v44, v45
	v_cvt_pk_bf16_f32 v43, v46, v47
	global_store_dwordx4 v[6:7], v[40:43], off
	v_lshl_add_u64 v[6:7], v[6:7], 0, s[6:7]
	global_load_dwordx4 v[16:19], v[4:5], off offset:-16
	global_load_dwordx4 v[20:23], v[4:5], off
	v_lshl_add_u64 v[4:5], v[4:5], 0, s[4:5]
	global_load_dwordx4 v[24:27], v[4:5], off offset:-16
	global_load_dwordx4 v[28:31], v[4:5], off
	v_lshl_add_u64 v[4:5], v[4:5], 0, s[4:5]
	global_load_dwordx4 v[32:35], v[4:5], off offset:-16
	global_load_dwordx4 v[36:39], v[4:5], off
	v_lshl_add_u64 v[4:5], v[4:5], 0, s[4:5]
	global_load_dwordx4 v[40:43], v[4:5], off offset:-16
	global_load_dwordx4 v[44:47], v[4:5], off
	v_lshl_add_u64 v[4:5], v[4:5], 0, s[4:5]
	s_waitcnt vmcnt(8)
	v_cvt_pk_bf16_f32 v48, v48, v49
	v_cvt_pk_bf16_f32 v49, v50, v51
	v_cvt_pk_bf16_f32 v50, v52, v53
	v_cvt_pk_bf16_f32 v51, v54, v55
	global_store_dwordx4 v[6:7], v[48:51], off
	v_lshl_add_u64 v[6:7], v[6:7], 0, s[6:7]
	v_cvt_pk_bf16_f32 v56, v56, v57
	v_cvt_pk_bf16_f32 v57, v58, v59
	v_cvt_pk_bf16_f32 v58, v60, v61
	v_cvt_pk_bf16_f32 v59, v62, v63
	global_store_dwordx4 v[6:7], v[56:59], off
	v_lshl_add_u64 v[6:7], v[6:7], 0, s[6:7]
	v_cvt_pk_bf16_f32 v64, v64, v65
	v_cvt_pk_bf16_f32 v65, v66, v67
	v_cvt_pk_bf16_f32 v66, v68, v69
	v_cvt_pk_bf16_f32 v67, v70, v71
	global_store_dwordx4 v[6:7], v[64:67], off
	v_lshl_add_u64 v[6:7], v[6:7], 0, s[6:7]
	v_cvt_pk_bf16_f32 v72, v72, v73
	v_cvt_pk_bf16_f32 v73, v74, v75
	v_cvt_pk_bf16_f32 v74, v76, v77
	v_cvt_pk_bf16_f32 v75, v78, v79
	global_store_dwordx4 v[6:7], v[72:75], off
	v_lshl_add_u64 v[6:7], v[6:7], 0, s[6:7]
	s_sub_u32 s8, s8, 1
	s_cmp_lg_u32 s8, 0
	s_cbranch_scc1 .Lxc_loop
	global_load_dwordx4 v[48:51], v[4:5], off offset:-16
	global_load_dwordx4 v[52:55], v[4:5], off
	v_lshl_add_u64 v[4:5], v[4:5], 0, s[4:5]
	global_load_dwordx4 v[56:59], v[4:5], off offset:-16
	global_load_dwordx4 v[60:63], v[4:5], off
	v_lshl_add_u64 v[4:5], v[4:5], 0, s[4:5]
	global_load_dwordx4 v[64:67], v[4:5], off offset:-16
	global_load_dwordx4 v[68:71], v[4:5], off
	v_lshl_add_u64 v[4:5], v[4:5], 0, s[4:5]
	global_load_dwordx4 v[72:75], v[4:5], off offset:-16
	global_load_dwordx4 v[76:79], v[4:5], off
	v_lshl_add_u64 v[4:5], v[4:5], 0, s[4:5]
	s_waitcnt vmcnt(8)
	v_cvt_pk_bf16_f32 v16, v16, v17
	v_cvt_pk_bf16_f32 v17, v18, v19
	v_cvt_pk_bf16_f32 v18, v20, v21
	v_cvt_pk_bf16_f32 v19, v22, v23
	global_store_dwordx4 v[6:7], v[16:19], off
	v_lshl_add_u64 v[6:7], v[6:7], 0, s[6:7]
	v_cvt_pk_bf16_f32 v24, v24, v25
	v_cvt_pk_bf16_f32 v25, v26, v27
	v_cvt_pk_bf16_f32 v26, v28, v29
	v_cvt_pk_bf16_f32 v27, v30, v31
	global_store_dwordx4 v[6:7], v[24:27], off
	v_lshl_add_u64 v[6:7], v[6:7], 0, s[6:7]
	v_cvt_pk_bf16_f32 v32, v32, v33
	v_cvt_pk_bf16_f32 v33, v34, v35
	v_cvt_pk_bf16_f32 v34, v36, v37
	v_cvt_pk_bf16_f32 v35, v38, v39
	global_store_dwordx4 v[6:7], v[32:35], off
	v_lshl_add_u64 v[6:7], v[6:7], 0, s[6:7]
	v_cvt_pk_bf16_f32 v40, v40, v41
	v_cvt_pk_bf16_f32 v41, v42, v43
	v_cvt_pk_bf16_f32 v42, v44, v45
	v_cvt_pk_bf16_f32 v43, v46, v47
	global_store_dwordx4 v[6:7], v[40:43], off
	v_lshl_add_u64 v[6:7], v[6:7], 0, s[6:7]
	s_waitcnt vmcnt(0)
	v_cvt_pk_bf16_f32 v48, v48, v49
	v_cvt_pk_bf16_f32 v49, v50, v51
	v_cvt_pk_bf16_f32 v50, v52, v53
	v_cvt_pk_bf16_f32 v51, v54, v55
	global_store_dwordx4 v[6:7], v[48:51], off
	v_lshl_add_u64 v[6:7], v[6:7], 0, s[6:7]
	v_cvt_pk_bf16_f32 v56, v56, v57
	v_cvt_pk_bf16_f32 v57, v58, v59
	v_cvt_pk_bf16_f32 v58, v60, v61
	v_cvt_pk_bf16_f32 v59, v62, v63
	global_store_dwordx4 v[6:7], v[56:59], off
	v_lshl_add_u64 v[6:7], v[6:7], 0, s[6:7]
	v_cvt_pk_bf16_f32 v64, v64, v65
	v_cvt_pk_bf16_f32 v65, v66, v67
	v_cvt_pk_bf16_f32 v66, v68, v69
	v_cvt_pk_bf16_f32 v67, v70, v71
	global_store_dwordx4 v[6:7], v[64:67], off
	v_lshl_add_u64 v[6:7], v[6:7], 0, s[6:7]
	v_cvt_pk_bf16_f32 v72, v72, v73
	v_cvt_pk_bf16_f32 v73, v74, v75
	v_cvt_pk_bf16_f32 v74, v76, v77
	v_cvt_pk_bf16_f32 v75, v78, v79
	global_store_dwordx4 v[6:7], v[72:75], off
	v_lshl_add_u64 v[6:7], v[6:7], 0, s[6:7]
	s_branch .LBB0_33
